# P1 K-loop: first iteration peeled with SrcC=0 on the first MFMA of each accumulator, 128 accumulator-zeroing v_mov per unit removed
# speedup vs baseline: 1.0181x; 1.0086x over previous
; #define PG8_STAGE(bufoff, gbase, voff) do { _Pragma("unroll") for (int _i = 0; _i < 2; ++_i) \
;         __builtin_amdgcn_global_load_lds((const unsigned*)((const char*)(gbase) + (voff)[_i]), (PG8_LAS unsigned*)(lds + (bufoff) + ldsw + _i * 8192), 16, 0, 0); } while (0)
; #define PG8_LDA(dst, b, h) do { _Pragma("unroll") for (int m = 0; m < 4; ++m) _Pragma("unroll") for (int k = 0; k < 2; ++k) dst[m][k] = *(const PG8_LAS bf16x8*)(lds + PG8_SA(b, h) + aoff + m * 2048 + k * 1024); } while (0)
; #define PG8_LDB(dst, b, h) do { _Pragma("unroll") for (int n = 0; n < 2; ++n) _Pragma("unroll") for (int k = 0; k < 2; ++k) dst[n][k] = *(const PG8_LAS bf16x8*)(lds + PG8_SB(b, h) + boff + n * 2048 + k * 1024); } while (0)
; #define PG8_MMA(ai, bj, At, Bt) do { __builtin_amdgcn_s_setprio(1); _Pragma("unroll") for (int m = 0; m < 4; ++m) _Pragma("unroll") for (int n = 0; n < 2; ++n) _Pragma("unroll") for (int k = 0; k < 2; ++k) \
;         acc[ai][bj][m][n] = __builtin_amdgcn_mfma_f32_16x16x32_bf16(Bt[n][k], At[m][k], acc[ai][bj][m][n], 0, 0, 0); __builtin_amdgcn_s_setprio(0); } while (0)
; #define PG8_WAIT_V(n) asm volatile("s_waitcnt vmcnt(" #n ")" ::: "memory")
; #define PG8_WAIT_L(n) asm volatile("s_waitcnt lgkmcnt(" #n ")" ::: "memory")
; #define PG8_BAR __builtin_amdgcn_s_barrier()
; #define PG8_SCHED __builtin_amdgcn_sched_barrier(0)
; template <class Epi, class Sched, bool ALIGN_EPI = false, bool SP2 = false, bool HS = false>
; __device__ __forceinline__ void gemm_phase(PG8_LAS unsigned char* lds, const Gemm g, const Sched& S, const Epi& E) {
;     ...
;     f32x4 acc[2][2][4][2];
; #pragma unroll
;     for (int a = 0; a < 2; ++a)
; #pragma unroll
;         for (int b = 0; b < 2; ++b)
; #pragma unroll
;             for (int m = 0; m < 4; ++m)
; #pragma unroll
;                 for (int n = 0; n < 2; ++n) acc[a][b][m][n] = (f32x4){0.f, 0.f, 0.f, 0.f};
;     ...
;             PG8_LDB(B0, 0, 0); PG8_LDB(B1, 0, 1); PG8_SCHED; PG8_LDA(At, 0, 0); PG8_STAGE(PG8_SA(1, 1), a1 + hstep, voffA);
;             PG8_WAIT_V(8); PG8_WAIT_L(0); PG8_BAR; PG8_MMA(0, 0, At, B0); PG8_MMA(0, 1, At, B1); PG8_BAR; PG8_SCHED;
;             PG8_LDA(At, 0, 1); PG8_STAGE(PG8_SB(0, 0), b2, voffB); PG8_STAGE(PG8_SB(0, 1), b2 + hstep, voffB); PG8_STAGE(PG8_SA(0, 0), a2, voffA);
;             PG8_WAIT_V(8); PG8_WAIT_L(0); PG8_BAR; PG8_MMA(1, 0, At, B0); PG8_MMA(1, 1, At, B1); PG8_BAR; PG8_SCHED;
.LBB0_261:
	s_ashr_i32 s45, s44, 31
	s_lshl_b64 s[0:1], s[44:45], 19
	s_add_u32 s48, s33, s0
	s_addc_u32 s49, s84, s1
	s_and_b64 s[0:1], s[46:47], exec
	s_cselect_b32 s0, s49, s9
	s_cselect_b32 s1, s48, s8
	s_ashr_i32 s37, s36, 31
	s_lshl_b64 s[52:53], s[36:37], 19
	s_add_u32 s54, s70, s52
	s_addc_u32 s55, s71, s53
	s_and_b64 s[52:53], s[46:47], exec
	s_cselect_b32 s2, s55, s11
	s_cselect_b32 s5, s54, s10
	s_add_u32 s8, s8, 0x40080
	s_addc_u32 s9, s9, 0
	s_add_u32 s7, s10, 0x100
	s_addc_u32 s37, s11, 0
	s_mov_b32 s45, -2
	ds_read_b128 v[4:7], v174
	ds_read_b128 v[12:15], v174 offset:1024
	ds_read_b128 v[136:139], v174 offset:2048
	ds_read_b128 v[140:143], v174 offset:3072
	ds_read_b128 v[158:161], v175
	ds_read_b128 v[162:165], v175 offset:1024
	ds_read_b128 v[182:185], v175 offset:2048
	ds_read_b128 v[188:191], v175 offset:3072
	s_add_u32 s10, s8, 0xfffc0080
	s_addc_u32 s11, s9, -1
	s_cmp_eq_u32 s45, 12
	s_cselect_b32 s57, s0, s11
	s_cselect_b32 s56, s1, s10
	s_cselect_b32 s11, s2, s37
	s_cselect_b32 s10, s5, s7
	v_lshl_add_u64 v[224:225], s[8:9], 0, v[154:155]
	s_add_i32 m0, s86, 0xc000
	ds_read_b128 v[192:195], v176
	ds_read_b128 v[196:199], v176 offset:1024
	ds_read_b128 v[200:203], v176 offset:2048
	ds_read_b128 v[204:207], v176 offset:3072
	ds_read_b128 v[208:211], v176 offset:4096
	ds_read_b128 v[212:215], v176 offset:5120
	ds_read_b128 v[216:219], v176 offset:6144
	ds_read_b128 v[220:223], v176 offset:7168
	global_load_lds_dwordx4 v[224:225], off
	v_lshl_add_u64 v[224:225], s[8:9], 0, v[156:157]
	s_add_i32 m0, s86, 0xe000
	s_nop 0
	global_load_lds_dwordx4 v[224:225], off
	s_waitcnt vmcnt(8)
	s_waitcnt lgkmcnt(0)
	s_barrier
	s_setprio 1
	s_waitcnt lgkmcnt(0)
	v_mfma_f32_16x16x32_bf16 v[8:11], v[4:7], v[192:195], 0
	v_mfma_f32_16x16x32_bf16 v[0:3], v[136:139], v[192:195], 0
	v_mfma_f32_16x16x32_bf16 v[124:127], v[4:7], v[200:203], 0
	v_mfma_f32_16x16x32_bf16 v[120:123], v[136:139], v[200:203], 0
	v_mfma_f32_16x16x32_bf16 v[108:111], v[4:7], v[208:211], 0
	v_mfma_f32_16x16x32_bf16 v[104:107], v[136:139], v[208:211], 0
	v_mfma_f32_16x16x32_bf16 v[92:95], v[4:7], v[216:219], 0
	v_mfma_f32_16x16x32_bf16 v[88:91], v[136:139], v[216:219], 0
	v_mfma_f32_16x16x32_bf16 v[8:11], v[12:15], v[196:199], v[8:11]
	v_mfma_f32_16x16x32_bf16 v[0:3], v[140:143], v[196:199], v[0:3]
	v_mfma_f32_16x16x32_bf16 v[124:127], v[12:15], v[204:207], v[124:127]
	v_mfma_f32_16x16x32_bf16 v[120:123], v[140:143], v[204:207], v[120:123]
	v_mfma_f32_16x16x32_bf16 v[108:111], v[12:15], v[212:215], v[108:111]
	v_mfma_f32_16x16x32_bf16 v[104:107], v[140:143], v[212:215], v[104:107]
	v_mfma_f32_16x16x32_bf16 v[92:95], v[12:15], v[220:223], v[92:95]
	v_mfma_f32_16x16x32_bf16 v[88:91], v[140:143], v[220:223], v[88:91]
	s_setprio 0
	s_setprio 1
	v_mfma_f32_16x16x32_bf16 v[132:135], v[158:161], v[192:195], 0
	v_mfma_f32_16x16x32_bf16 v[128:131], v[182:185], v[192:195], 0
	v_mfma_f32_16x16x32_bf16 v[116:119], v[158:161], v[200:203], 0
	v_mfma_f32_16x16x32_bf16 v[112:115], v[182:185], v[200:203], 0
	v_mfma_f32_16x16x32_bf16 v[100:103], v[158:161], v[208:211], 0
	v_mfma_f32_16x16x32_bf16 v[96:99], v[182:185], v[208:211], 0
	v_mfma_f32_16x16x32_bf16 v[84:87], v[158:161], v[216:219], 0
	v_mfma_f32_16x16x32_bf16 v[80:83], v[182:185], v[216:219], 0
	v_mfma_f32_16x16x32_bf16 v[132:135], v[162:165], v[196:199], v[132:135]
	v_mfma_f32_16x16x32_bf16 v[128:131], v[188:191], v[196:199], v[128:131]
	v_mfma_f32_16x16x32_bf16 v[116:119], v[162:165], v[204:207], v[116:119]
	v_mfma_f32_16x16x32_bf16 v[112:115], v[188:191], v[204:207], v[112:115]
	v_mfma_f32_16x16x32_bf16 v[100:103], v[162:165], v[212:215], v[100:103]
	v_mfma_f32_16x16x32_bf16 v[96:99], v[188:191], v[212:215], v[96:99]
	v_mfma_f32_16x16x32_bf16 v[84:87], v[162:165], v[220:223], v[84:87]
	v_mfma_f32_16x16x32_bf16 v[80:83], v[188:191], v[220:223], v[80:83]
	s_setprio 0
	s_barrier
	s_add_i32 s52, s42, s85
	v_lshl_add_u64 v[224:225], s[10:11], 0, v[146:147]
	s_mov_b32 m0, s52
	ds_read_b128 v[192:195], v176 offset:16384
	ds_read_b128 v[196:199], v176 offset:17408
	ds_read_b128 v[200:203], v176 offset:18432
	ds_read_b128 v[204:207], v176 offset:19456
	ds_read_b128 v[208:211], v176 offset:20480
	ds_read_b128 v[212:215], v176 offset:21504
	ds_read_b128 v[216:219], v176 offset:22528
	ds_read_b128 v[220:223], v176 offset:23552
	global_load_lds_dwordx4 v[224:225], off
	s_add_i32 m0, s52, 0x2000
	s_add_u32 s52, s10, 0x40000
	v_lshl_add_u64 v[226:227], s[10:11], 0, v[150:151]
	s_addc_u32 s53, s11, 0
	s_add_i32 s58, s43, s85
	global_load_lds_dwordx4 v[226:227], off
	v_lshl_add_u64 v[228:229], s[52:53], 0, v[146:147]
	s_mov_b32 m0, s58
	v_lshl_add_u64 v[230:231], s[56:57], 0, v[148:149]
	global_load_lds_dwordx4 v[228:229], off
	v_lshl_add_u64 v[228:229], s[52:53], 0, v[150:151]
	s_add_i32 m0, s58, 0x2000
	s_nop 0
	global_load_lds_dwordx4 v[228:229], off
	v_lshl_add_u64 v[228:229], s[56:57], 0, v[144:145]
	s_mov_b32 m0, s86
	s_nop 0
	global_load_lds_dwordx4 v[228:229], off
	s_mov_b32 m0, s87
	s_nop 0
	global_load_lds_dwordx4 v[230:231], off
	s_waitcnt vmcnt(8)
	s_waitcnt lgkmcnt(0)
	s_barrier
; #define PG8_STAGE(bufoff, gbase, voff) do { _Pragma("unroll") for (int _i = 0; _i < 2; ++_i) \
;         __builtin_amdgcn_global_load_lds((const unsigned*)((const char*)(gbase) + (voff)[_i]), (PG8_LAS unsigned*)(lds + (bufoff) + ldsw + _i * 8192), 16, 0, 0); } while (0)
; #define PG8_LDA(dst, b, h) do { _Pragma("unroll") for (int m = 0; m < 4; ++m) _Pragma("unroll") for (int k = 0; k < 2; ++k) dst[m][k] = *(const PG8_LAS bf16x8*)(lds + PG8_SA(b, h) + aoff + m * 2048 + k * 1024); } while (0)
; #define PG8_LDB(dst, b, h) do { _Pragma("unroll") for (int n = 0; n < 2; ++n) _Pragma("unroll") for (int k = 0; k < 2; ++k) dst[n][k] = *(const PG8_LAS bf16x8*)(lds + PG8_SB(b, h) + boff + n * 2048 + k * 1024); } while (0)
; #define PG8_MMA(ai, bj, At, Bt) do { __builtin_amdgcn_s_setprio(1); _Pragma("unroll") for (int m = 0; m < 4; ++m) _Pragma("unroll") for (int n = 0; n < 2; ++n) _Pragma("unroll") for (int k = 0; k < 2; ++k) \
;         acc[ai][bj][m][n] = __builtin_amdgcn_mfma_f32_16x16x32_bf16(Bt[n][k], At[m][k], acc[ai][bj][m][n], 0, 0, 0); __builtin_amdgcn_s_setprio(0); } while (0)
; #define PG8_WAIT_V(n) asm volatile("s_waitcnt vmcnt(" #n ")" ::: "memory")
; #define PG8_WAIT_L(n) asm volatile("s_waitcnt lgkmcnt(" #n ")" ::: "memory")
; #define PG8_BAR __builtin_amdgcn_s_barrier()
; #define PG8_SCHED __builtin_amdgcn_sched_barrier(0)
; template <class Epi, class Sched, bool ALIGN_EPI = false, bool SP2 = false, bool HS = false>
; __device__ __forceinline__ void gemm_phase(PG8_LAS unsigned char* lds, const Gemm g, const Sched& S, const Epi& E) {
;     ...
;             PG8_WAIT_V(8); PG8_WAIT_L(0); PG8_BAR; PG8_MMA(1, 0, At, B0); PG8_MMA(1, 1, At, B1); PG8_BAR; PG8_SCHED;
;             PG8_LDB(B0, 1, 0); PG8_LDB(B1, 1, 1); PG8_SCHED; PG8_LDA(At, 1, 0); PG8_STAGE(PG8_SA(0, 1), a2 + hstep, voffA);
;             PG8_WAIT_V(8); PG8_WAIT_L(0); PG8_BAR; PG8_MMA(0, 0, At, B0); PG8_MMA(0, 1, At, B1); PG8_BAR; PG8_SCHED;
;             PG8_LDA(At, 1, 1); PG8_STAGE(PG8_SB(1, 0), b3, voffB); PG8_STAGE(PG8_SB(1, 1), b3 + hstep, voffB); PG8_STAGE(PG8_SA(1, 0), a3, voffA);
;             PG8_WAIT_V(8); PG8_WAIT_L(0); PG8_BAR; PG8_MMA(1, 0, At, B0); PG8_MMA(1, 1, At, B1); PG8_BAR; PG8_SCHED;
	s_setprio 1
	s_waitcnt lgkmcnt(0)
	v_mfma_f32_16x16x32_bf16 v[76:79], v[4:7], v[192:195], 0
	v_mfma_f32_16x16x32_bf16 v[72:75], v[136:139], v[192:195], 0
	v_mfma_f32_16x16x32_bf16 v[60:63], v[4:7], v[200:203], 0
	v_mfma_f32_16x16x32_bf16 v[56:59], v[136:139], v[200:203], 0
	v_mfma_f32_16x16x32_bf16 v[44:47], v[4:7], v[208:211], 0
	v_mfma_f32_16x16x32_bf16 v[40:43], v[136:139], v[208:211], 0
	v_mfma_f32_16x16x32_bf16 v[4:7], v[4:7], v[216:219], 0
	v_mfma_f32_16x16x32_bf16 v[76:79], v[12:15], v[196:199], v[76:79]
	v_mfma_f32_16x16x32_bf16 v[72:75], v[140:143], v[196:199], v[72:75]
	v_mfma_f32_16x16x32_bf16 v[60:63], v[12:15], v[204:207], v[60:63]
	v_mfma_f32_16x16x32_bf16 v[56:59], v[140:143], v[204:207], v[56:59]
	v_mfma_f32_16x16x32_bf16 v[44:47], v[12:15], v[212:215], v[44:47]
	v_mfma_f32_16x16x32_bf16 v[40:43], v[140:143], v[212:215], v[40:43]
	v_mfma_f32_16x16x32_bf16 v[4:7], v[12:15], v[220:223], v[4:7]
	v_mfma_f32_16x16x32_bf16 v[12:15], v[136:139], v[216:219], 0
	v_mfma_f32_16x16x32_bf16 v[12:15], v[140:143], v[220:223], v[12:15]
	s_setprio 0
	s_setprio 1
	v_mfma_f32_16x16x32_bf16 v[24:27], v[158:161], v[192:195], 0
	v_mfma_f32_16x16x32_bf16 v[68:71], v[162:165], v[196:199], v[24:27]
	v_mfma_f32_16x16x32_bf16 v[24:27], v[182:185], v[192:195], 0
	v_mfma_f32_16x16x32_bf16 v[64:67], v[188:191], v[196:199], v[24:27]
	v_mfma_f32_16x16x32_bf16 v[24:27], v[158:161], v[200:203], 0
	v_mfma_f32_16x16x32_bf16 v[52:55], v[162:165], v[204:207], v[24:27]
	v_mfma_f32_16x16x32_bf16 v[24:27], v[182:185], v[200:203], 0
	v_mfma_f32_16x16x32_bf16 v[48:51], v[188:191], v[204:207], v[24:27]
	v_mfma_f32_16x16x32_bf16 v[24:27], v[158:161], v[208:211], 0
	v_mfma_f32_16x16x32_bf16 v[36:39], v[162:165], v[212:215], v[24:27]
	v_mfma_f32_16x16x32_bf16 v[24:27], v[182:185], v[208:211], 0
	v_mfma_f32_16x16x32_bf16 v[20:23], v[158:161], v[216:219], 0
	v_mfma_f32_16x16x32_bf16 v[16:19], v[182:185], v[216:219], 0
	v_mfma_f32_16x16x32_bf16 v[32:35], v[188:191], v[212:215], v[24:27]
	v_mfma_f32_16x16x32_bf16 v[20:23], v[162:165], v[220:223], v[20:23]
	v_mfma_f32_16x16x32_bf16 v[16:19], v[188:191], v[220:223], v[16:19]
	s_setprio 0
	s_barrier
	s_add_i32 s58, 0, 0x18000
	s_add_i32 s59, 0, 0x1c000
	v_add_u32_e32 v140, s58, v169
	v_add_u32_e32 v152, s59, v169
	ds_read_b128 v[24:27], v140
	ds_read_b128 v[28:31], v140 offset:1024
	ds_read_b128 v[136:139], v140 offset:2048
	ds_read_b128 v[140:143], v140 offset:3072
	ds_read_b128 v[158:161], v152
	ds_read_b128 v[162:165], v152 offset:1024
	ds_read_b128 v[182:185], v152 offset:2048
	ds_read_b128 v[188:191], v152 offset:3072
	s_add_u32 s52, s56, 0x40000
	s_addc_u32 s53, s57, 0
	s_mov_b32 m0, s88
	v_lshl_add_u64 v[232:233], s[52:53], 0, v[144:145]
	ds_read_b128 v[192:195], v176 offset:32768
	ds_read_b128 v[196:199], v176 offset:33792
	ds_read_b128 v[200:203], v176 offset:34816
	ds_read_b128 v[204:207], v176 offset:35840
	ds_read_b128 v[208:211], v176 offset:36864
	ds_read_b128 v[212:215], v176 offset:37888
	ds_read_b128 v[216:219], v176 offset:38912
	ds_read_b128 v[220:223], v176 offset:39936
	global_load_lds_dwordx4 v[232:233], off
	v_lshl_add_u64 v[232:233], s[52:53], 0, v[148:149]
	s_mov_b32 m0, s89
	s_nop 0
	global_load_lds_dwordx4 v[232:233], off
	s_waitcnt vmcnt(8)
	s_waitcnt lgkmcnt(0)
	s_barrier
	s_setprio 1
	s_waitcnt lgkmcnt(0)
	v_mfma_f32_16x16x32_bf16 v[8:11], v[24:27], v[192:195], v[8:11]
	v_mfma_f32_16x16x32_bf16 v[0:3], v[136:139], v[192:195], v[0:3]
	v_mfma_f32_16x16x32_bf16 v[124:127], v[24:27], v[200:203], v[124:127]
	v_mfma_f32_16x16x32_bf16 v[120:123], v[136:139], v[200:203], v[120:123]
	v_mfma_f32_16x16x32_bf16 v[108:111], v[24:27], v[208:211], v[108:111]
	v_mfma_f32_16x16x32_bf16 v[104:107], v[136:139], v[208:211], v[104:107]
	v_mfma_f32_16x16x32_bf16 v[92:95], v[24:27], v[216:219], v[92:95]
	v_mfma_f32_16x16x32_bf16 v[88:91], v[136:139], v[216:219], v[88:91]
	v_mfma_f32_16x16x32_bf16 v[8:11], v[28:31], v[196:199], v[8:11]
	v_mfma_f32_16x16x32_bf16 v[0:3], v[140:143], v[196:199], v[0:3]
	v_mfma_f32_16x16x32_bf16 v[124:127], v[28:31], v[204:207], v[124:127]
	v_mfma_f32_16x16x32_bf16 v[120:123], v[140:143], v[204:207], v[120:123]
	v_mfma_f32_16x16x32_bf16 v[108:111], v[28:31], v[212:215], v[108:111]
	v_mfma_f32_16x16x32_bf16 v[104:107], v[140:143], v[212:215], v[104:107]
	v_mfma_f32_16x16x32_bf16 v[92:95], v[28:31], v[220:223], v[92:95]
	v_mfma_f32_16x16x32_bf16 v[88:91], v[140:143], v[220:223], v[88:91]
	s_setprio 0
	s_setprio 1
	v_mfma_f32_16x16x32_bf16 v[132:135], v[158:161], v[192:195], v[132:135]
	v_mfma_f32_16x16x32_bf16 v[128:131], v[182:185], v[192:195], v[128:131]
	v_mfma_f32_16x16x32_bf16 v[116:119], v[158:161], v[200:203], v[116:119]
	v_mfma_f32_16x16x32_bf16 v[112:115], v[182:185], v[200:203], v[112:115]
	v_mfma_f32_16x16x32_bf16 v[100:103], v[158:161], v[208:211], v[100:103]
	v_mfma_f32_16x16x32_bf16 v[96:99], v[182:185], v[208:211], v[96:99]
	v_mfma_f32_16x16x32_bf16 v[84:87], v[158:161], v[216:219], v[84:87]
	v_mfma_f32_16x16x32_bf16 v[80:83], v[182:185], v[216:219], v[80:83]
	v_mfma_f32_16x16x32_bf16 v[132:135], v[162:165], v[196:199], v[132:135]
	v_mfma_f32_16x16x32_bf16 v[128:131], v[188:191], v[196:199], v[128:131]
	v_mfma_f32_16x16x32_bf16 v[116:119], v[162:165], v[204:207], v[116:119]
	v_mfma_f32_16x16x32_bf16 v[112:115], v[188:191], v[204:207], v[112:115]
	v_mfma_f32_16x16x32_bf16 v[100:103], v[162:165], v[212:215], v[100:103]
	v_mfma_f32_16x16x32_bf16 v[96:99], v[188:191], v[212:215], v[96:99]
	v_mfma_f32_16x16x32_bf16 v[84:87], v[162:165], v[220:223], v[84:87]
	v_mfma_f32_16x16x32_bf16 v[80:83], v[188:191], v[220:223], v[80:83]
	s_setprio 0
	s_barrier
; #define PG8_STAGE(bufoff, gbase, voff) do { _Pragma("unroll") for (int _i = 0; _i < 2; ++_i) \
;         __builtin_amdgcn_global_load_lds((const unsigned*)((const char*)(gbase) + (voff)[_i]), (PG8_LAS unsigned*)(lds + (bufoff) + ldsw + _i * 8192), 16, 0, 0); } while (0)
; #define PG8_LDA(dst, b, h) do { _Pragma("unroll") for (int m = 0; m < 4; ++m) _Pragma("unroll") for (int k = 0; k < 2; ++k) dst[m][k] = *(const PG8_LAS bf16x8*)(lds + PG8_SA(b, h) + aoff + m * 2048 + k * 1024); } while (0)
; #define PG8_LDB(dst, b, h) do { _Pragma("unroll") for (int n = 0; n < 2; ++n) _Pragma("unroll") for (int k = 0; k < 2; ++k) dst[n][k] = *(const PG8_LAS bf16x8*)(lds + PG8_SB(b, h) + boff + n * 2048 + k * 1024); } while (0)
; #define PG8_MMA(ai, bj, At, Bt) do { __builtin_amdgcn_s_setprio(1); _Pragma("unroll") for (int m = 0; m < 4; ++m) _Pragma("unroll") for (int n = 0; n < 2; ++n) _Pragma("unroll") for (int k = 0; k < 2; ++k) \
;         acc[ai][bj][m][n] = __builtin_amdgcn_mfma_f32_16x16x32_bf16(Bt[n][k], At[m][k], acc[ai][bj][m][n], 0, 0, 0); __builtin_amdgcn_s_setprio(0); } while (0)
; #define PG8_WAIT_V(n) asm volatile("s_waitcnt vmcnt(" #n ")" ::: "memory")
; #define PG8_WAIT_L(n) asm volatile("s_waitcnt lgkmcnt(" #n ")" ::: "memory")
; #define PG8_BAR __builtin_amdgcn_s_barrier()
; #define PG8_SCHED __builtin_amdgcn_sched_barrier(0)
; template <class Epi, class Sched, bool ALIGN_EPI = false, bool SP2 = false, bool HS = false>
; __device__ __forceinline__ void gemm_phase(PG8_LAS unsigned char* lds, const Gemm g, const Sched& S, const Epi& E) {
;     ...
;             PG8_LDB(B0, 1, 0); PG8_LDB(B1, 1, 1); PG8_SCHED; PG8_LDA(At, 1, 0); PG8_STAGE(PG8_SA(0, 1), a2 + hstep, voffA);
;             PG8_WAIT_V(8); PG8_WAIT_L(0); PG8_BAR; PG8_MMA(0, 0, At, B0); PG8_MMA(0, 1, At, B1); PG8_BAR; PG8_SCHED;
;             PG8_LDA(At, 1, 1); PG8_STAGE(PG8_SB(1, 0), b3, voffB); PG8_STAGE(PG8_SB(1, 1), b3 + hstep, voffB); PG8_STAGE(PG8_SA(1, 0), a3, voffA);
;             PG8_WAIT_V(8); PG8_WAIT_L(0); PG8_BAR; PG8_MMA(1, 0, At, B0); PG8_MMA(1, 1, At, B1); PG8_BAR; PG8_SCHED;
	s_add_i32 s52, s58, s85
	v_lshl_add_u64 v[224:225], v[224:225], 0, s[14:15]
	s_mov_b32 m0, s52
	ds_read_b128 v[192:195], v176 offset:49152
	ds_read_b128 v[196:199], v176 offset:50176
	ds_read_b128 v[200:203], v176 offset:51200
	ds_read_b128 v[204:207], v176 offset:52224
	ds_read_b128 v[208:211], v176 offset:53248
	ds_read_b128 v[212:215], v176 offset:54272
	ds_read_b128 v[216:219], v176 offset:55296
	ds_read_b128 v[220:223], v176 offset:56320
	global_load_lds_dwordx4 v[224:225], off
	s_add_i32 m0, s52, 0x2000
	s_add_u32 s10, s10, 0x40080
	v_lshl_add_u64 v[224:225], v[226:227], 0, s[14:15]
	s_addc_u32 s11, s11, 0
	s_add_i32 s52, s59, s85
	global_load_lds_dwordx4 v[224:225], off
	v_lshl_add_u64 v[224:225], s[10:11], 0, v[146:147]
	s_mov_b32 m0, s52
	s_nop 0
	global_load_lds_dwordx4 v[224:225], off
	v_lshl_add_u64 v[224:225], s[10:11], 0, v[150:151]
	s_add_i32 m0, s52, 0x2000
	s_nop 0
	global_load_lds_dwordx4 v[224:225], off
	v_lshl_add_u64 v[224:225], v[228:229], 0, s[14:15]
	s_mov_b32 m0, s95
	s_nop 0
	global_load_lds_dwordx4 v[224:225], off
	v_lshl_add_u64 v[224:225], v[230:231], 0, s[14:15]
	s_mov_b32 m0, s96
	s_nop 0
	global_load_lds_dwordx4 v[224:225], off
	s_waitcnt vmcnt(8)
	s_waitcnt lgkmcnt(0)
	s_barrier
	s_setprio 1
	s_waitcnt lgkmcnt(0)
	v_mfma_f32_16x16x32_bf16 v[76:79], v[24:27], v[192:195], v[76:79]
	v_mfma_f32_16x16x32_bf16 v[60:63], v[24:27], v[200:203], v[60:63]
	v_mfma_f32_16x16x32_bf16 v[44:47], v[24:27], v[208:211], v[44:47]
	v_mfma_f32_16x16x32_bf16 v[4:7], v[24:27], v[216:219], v[4:7]
	v_mfma_f32_16x16x32_bf16 v[76:79], v[28:31], v[196:199], v[76:79]
	v_mfma_f32_16x16x32_bf16 v[72:75], v[136:139], v[192:195], v[72:75]
	v_mfma_f32_16x16x32_bf16 v[60:63], v[28:31], v[204:207], v[60:63]
	v_mfma_f32_16x16x32_bf16 v[56:59], v[136:139], v[200:203], v[56:59]
	v_mfma_f32_16x16x32_bf16 v[44:47], v[28:31], v[212:215], v[44:47]
	v_mfma_f32_16x16x32_bf16 v[40:43], v[136:139], v[208:211], v[40:43]
	v_mfma_f32_16x16x32_bf16 v[28:31], v[28:31], v[220:223], v[4:7]
	v_mfma_f32_16x16x32_bf16 v[4:7], v[136:139], v[216:219], v[12:15]
	v_mfma_f32_16x16x32_bf16 v[72:75], v[140:143], v[196:199], v[72:75]
	v_mfma_f32_16x16x32_bf16 v[56:59], v[140:143], v[204:207], v[56:59]
	v_mfma_f32_16x16x32_bf16 v[40:43], v[140:143], v[212:215], v[40:43]
	v_mfma_f32_16x16x32_bf16 v[24:27], v[140:143], v[220:223], v[4:7]
	s_setprio 0
	s_setprio 1
	v_mfma_f32_16x16x32_bf16 v[4:7], v[158:161], v[192:195], v[68:71]
	v_mfma_f32_16x16x32_bf16 v[68:71], v[162:165], v[196:199], v[4:7]
	v_mfma_f32_16x16x32_bf16 v[4:7], v[182:185], v[192:195], v[64:67]
	v_mfma_f32_16x16x32_bf16 v[64:67], v[188:191], v[196:199], v[4:7]
	v_mfma_f32_16x16x32_bf16 v[4:7], v[158:161], v[200:203], v[52:55]
	v_mfma_f32_16x16x32_bf16 v[52:55], v[162:165], v[204:207], v[4:7]
	v_mfma_f32_16x16x32_bf16 v[4:7], v[182:185], v[200:203], v[48:51]
	v_mfma_f32_16x16x32_bf16 v[48:51], v[188:191], v[204:207], v[4:7]
	v_mfma_f32_16x16x32_bf16 v[4:7], v[158:161], v[208:211], v[36:39]
	v_mfma_f32_16x16x32_bf16 v[36:39], v[162:165], v[212:215], v[4:7]
	v_mfma_f32_16x16x32_bf16 v[4:7], v[182:185], v[208:211], v[32:35]
	v_mfma_f32_16x16x32_bf16 v[32:35], v[188:191], v[212:215], v[4:7]
	v_mfma_f32_16x16x32_bf16 v[4:7], v[158:161], v[216:219], v[20:23]
	v_mfma_f32_16x16x32_bf16 v[20:23], v[162:165], v[220:223], v[4:7]
	v_mfma_f32_16x16x32_bf16 v[4:7], v[182:185], v[216:219], v[16:19]
	v_mfma_f32_16x16x32_bf16 v[16:19], v[188:191], v[220:223], v[4:7]
	s_setprio 0
	s_barrier
	s_add_i32 s45, s45, 2
	s_add_u32 s8, s8, 0x100
	s_addc_u32 s9, s9, 0
	s_add_u32 s7, s7, 0x100
	s_addc_u32 s37, s37, 0
	s_cmp_gt_u32 s45, 13
